# P5: tail K-slice unit runs before the main tile (overlaps other workgroups' main epilogue), on top of rotary prefetch + P5 4-slice tail
# baseline (speedup 1.0000x reference)
.LBB0_956:
	v_lshrrev_b32_e32 v1, 5, v208
	v_lshrrev_b32_e32 v3, 1, v208
	v_and_b32_e32 v1, 4, v1
	v_bfe_u32 v2, v208, 2, 2
	v_and_b32_e32 v165, 24, v3
	v_lshlrev_b32_e32 v136, 4, v208
	v_and_b32_e32 v0, 32, v208
	v_bfe_u32 v10, v208, 2, 4
	v_or3_b32 v1, v1, v2, v165
	v_lshrrev_b32_e32 v2, 3, v208
	s_movk_i32 s3, 0x70
	v_bitop3_b32 v8, v136, v0, 48 bitop3:0x6c
	v_and_b32_e32 v9, 64, v208
	v_and_or_b32 v3, v2, s3, v10
	s_movk_i32 s3, 0x60
	v_or_b32_e32 v0, v8, v9
	v_and_or_b32 v2, v2, s3, v1
	v_add_u32_e32 v11, 0x2000, v136
	s_add_u32 s52, s96, 0xc00000
	v_lshl_or_b32 v140, v2, 12, v0
	v_lshrrev_b32_e32 v2, 7, v11
	s_movk_i32 s3, 0xf0
	s_addc_u32 s53, s97, 0
	v_lshl_or_b32 v138, v3, 12, v0
	v_and_or_b32 v3, v2, s3, v10
	s_movk_i32 s3, 0xe0
	s_add_u32 s54, s96, 0x400000
	v_and_or_b32 v1, v2, s3, v1
	s_addc_u32 s55, s97, 0
	v_lshl_or_b32 v142, v3, 12, v0
	v_lshl_or_b32 v144, v1, 12, v0
	v_lshlrev_b32_e32 v0, 6, v208
	s_add_u32 s8, s96, 0x2f00000
	v_and_b32_e32 v137, 0x3c0, v0
	v_lshlrev_b32_e32 v0, 2, v208
	s_addc_u32 s9, s97, 0
	v_and_b32_e32 v164, 15, v208
	v_and_b32_e32 v166, 32, v0
	s_mov_b64 s[92:93], s[0:1]
	s_mov_b32 s94, s2
	s_mov_b32 s95, s18
	s_mov_b32 s100, s24
	s_mov_b32 s101, s26
	s_mov_b32 s32, s36
	s_nop 0
	v_mov_b32_e32 v232, v8
	v_mov_b32_e32 v233, v9
	v_mov_b32_e32 v234, v10
	v_mov_b32_e32 v235, v11
	v_mov_b32_e32 v236, v137
	v_mov_b32_e32 v237, v166
	s_nop 0
	s_branch .Lmy_p5_early
.Lmy_p5_back:
	s_mov_b64 s[0:1], s[92:93]
	s_mov_b32 s2, s94
	s_mov_b32 s18, s95
	s_mov_b32 s24, s100
	s_mov_b32 s26, s101
	s_mov_b32 s36, s32
	s_nop 0
	v_mov_b32_e32 v8, v232
	v_mov_b32_e32 v9, v233
	v_mov_b32_e32 v10, v234
	v_mov_b32_e32 v11, v235
	v_mov_b32_e32 v137, v236
	v_mov_b32_e32 v166, v237
	s_andn2_b64 vcc, exec, s[0:1]
	s_cbranch_vccnz .LBB0_1068
	s_lshr_b32 s0, s2, 6
	s_ashr_i32 s27, s26, 31
	s_ashr_i32 s25, s24, 31
	s_lshr_b32 s1, s2, 8
	s_lshl_b32 s37, s0, 10
	s_lshl_b64 s[10:11], s[26:27], 20
	s_lshl_b64 s[12:13], s[24:25], 20
	s_add_u32 s30, s54, s12
	s_addc_u32 s31, s55, s13
	s_add_i32 s38, s37, 0
	s_add_i32 m0, s38, 0x10000
	v_mov_b32_e32 v147, 0
	global_load_lds_dwordx4 v140, s[30:31]
	s_add_i32 m0, s38, 0x12000
	s_add_u32 s12, s30, 0x80000
	global_load_lds_dwordx4 v144, s[30:31]
	s_addc_u32 s13, s31, 0
	s_add_i32 m0, s38, 0x14000
	v_mov_b32_e32 v141, v147
	global_load_lds_dwordx4 v140, s[12:13]
	s_add_i32 m0, s38, 0x16000
	s_add_u32 s28, s52, s10
	s_addc_u32 s29, s53, s11
	s_add_i32 s39, s38, 0x2000
	global_load_lds_dwordx4 v144, s[12:13]
	s_mov_b32 m0, s38
	s_add_u32 s10, s28, 0x80000
	global_load_lds_dwordx4 v138, s[28:29]
	s_mov_b32 m0, s39
	s_addc_u32 s11, s29, 0
	s_add_i32 s40, s38, 0x4000
	global_load_lds_dwordx4 v142, s[28:29]
	s_mov_b32 m0, s40
	s_add_i32 s41, s38, 0x6000
	global_load_lds_dwordx4 v138, s[10:11]
	s_mov_b32 m0, s41
	v_mov_b32_e32 v145, v147
	global_load_lds_dwordx4 v142, s[10:11]
	v_mov_b32_e32 v139, v147
	v_mov_b32_e32 v143, v147
	s_cmp_eq_u32 s1, 1
	s_mov_b32 s7, 0
	v_lshl_add_u64 v[6:7], s[30:31], 0, v[140:141]
	v_lshl_add_u64 v[4:5], s[30:31], 0, v[144:145]
	v_lshl_add_u64 v[0:1], s[28:29], 0, v[138:139]
	s_cselect_b64 s[10:11], -1, 0
	s_cmp_lg_u32 s1, 1
	v_lshl_add_u64 v[2:3], s[28:29], 0, v[142:143]
	s_cbranch_scc1 .LBB0_959
	s_barrier

.LBB0_1068:
	s_cmp_eq_u32 s36, 0
	s_cbranch_scc1 .LBB0_1156
	s_add_u32 s10, s96, 0x14ec0000
	s_addc_u32 s11, s97, 0
	s_lshl_b32 s7, s36, 3
	s_cmp_lt_i32 s88, s7
	s_cselect_b64 s[12:13], -1, 0
	s_lshl_b32 s98, s36, 2
	s_cmp_ge_i32 s88, s98
	v_readfirstlane_b32 s0, v208
	s_branch .LBB0_1089

.LBB0_1088:
	s_waitcnt vmcnt(0)
	s_mov_b32 s61, s78
	s_mov_b64 s[62:63], s[82:83]
	s_barrier
	s_nop 0
	s_branch .Lmy_p5_back
